# layer-0 gMLP units: unit-to-workgroup order reversed so the workgroups that ran the extra context attention units do not also get the third gMLP unit
# baseline (speedup 1.0000x reference)
;     __device__ __forceinline__ bf16_t* bfp(size_t off) const { return (bf16_t*)(ws + off); }
; __device__ void gmlp_unit(const Ctx& c, int tid, int l, int ch, int g, unsigned short* T) {
;     const KParams pk = c.p;
;     const int lane = tid & 63, wave = tid >> 6;
;     const int r32 = lane & 31, hi = lane >> 5, pblk = wave >> 1, cb0 = (wave & 1) * 2;
;     const float* wsr = pk->in[10] + ((size_t)(l * 8 + g) * 128 + pblk * 32 + r32) * 128 + hi * 8;
;     const bf16_t* vn = c.bfp(WS_VN) + (size_t)(ch * 128) * 1024 + g * 128;
;     bf16_t* AM0 = c.bfp(WS_AM);
;     {
;         const int q = tid >> 4, c8 = (tid & 15) * 8;
;         u32x4 v[4];
; #pragma unroll
;         for (int ps = 0; ps < 4; ++ps) v[ps] = *(const u32x4*)(vn + (size_t)(q + 32 * ps) * 1024 + c8);
; #pragma unroll
;         for (int ps = 0; ps < 4; ++ps) { unsigned short* d = T + (q + 32 * ps) * 132 + c8; *(u32x2*)d = (u32x2){v[ps].x, v[ps].y}; *(u32x2*)(d + 4) = (u32x2){v[ps].z, v[ps].w}; }
; __device__ void phase_attn(const Ctx& c, int l, bool with_ctx, char* lds, bool skip_gmlp) {
;     ...
;     if (skip_gmlp) return;
;     const int nch = with_ctx ? 72 : 64;
;     ...
;     int t2 = c.tid; asm volatile("" : "+v"(t2));
;     for (int u = c.bid; u < nch * 8; u += c.G) gmlp_unit(c, t2, l, u >> 3, u & 7, (unsigned short*)lds);
.LBB0_462:
	s_sub_i32 s35, s38, s35
	s_add_i32 s35, s35, -1
	s_andn2_b64 vcc, exec, s[10:11]
	s_cbranch_vccnz .LBB0_465
	v_ashrrev_i32_e32 v2, 2, v194
	v_and_b32_e32 v5, 0xffffffe0, v2
	v_ashrrev_i32_e32 v2, 4, v194
	v_lshlrev_b32_e32 v3, 3, v194
	v_and_b32_e32 v4, 0x78, v3
	v_ashrrev_i32_e32 v3, 31, v2
	v_lshlrev_b64 v[36:37], 11, v[2:3]
	s_mov_b64 s[4:5], 0x10000
	v_lshl_add_u64 v[38:39], v[36:37], 0, s[4:5]
	s_mov_b64 s[4:5], 0x20000
	v_lshl_add_u64 v[40:41], v[36:37], 0, s[4:5]
	s_mov_b64 s[4:5], 0x30000
	v_lshl_add_u64 v[42:43], v[36:37], 0, s[4:5]
	s_movk_i32 s4, 0x108
	v_and_b32_e32 v0, 31, v194
	v_bfe_u32 v1, v194, 5, 1
	v_mul_lo_u32 v8, v2, s4
	v_and_b32_e32 v2, 64, v194
	s_movk_i32 s4, 0x840
	v_mad_u32_u24 v6, v1, s4, 0
	v_lshlrev_b32_e32 v7, 1, v2
	v_lshlrev_b32_e32 v9, 1, v0
	v_lshl_or_b32 v44, v1, 2, v5
	v_add3_u32 v90, v6, v7, v9
	v_or_b32_e32 v6, 1, v44
	v_ashrrev_i32_e32 v7, 31, v6
	v_lshlrev_b64 v[48:49], 11, v[6:7]
	v_or_b32_e32 v6, 2, v44
	v_ashrrev_i32_e32 v7, 31, v6
	v_lshlrev_b64 v[50:51], 11, v[6:7]
	v_or_b32_e32 v6, 3, v44
	v_ashrrev_i32_e32 v7, 31, v6
	v_lshlrev_b64 v[52:53], 11, v[6:7]
	v_or_b32_e32 v6, 8, v44
	v_ashrrev_i32_e32 v7, 31, v6
	v_lshlrev_b64 v[54:55], 11, v[6:7]
	v_or_b32_e32 v6, 9, v44
	v_ashrrev_i32_e32 v7, 31, v6
	v_lshlrev_b64 v[56:57], 11, v[6:7]
	v_or_b32_e32 v6, 10, v44
	v_ashrrev_i32_e32 v7, 31, v6
	v_lshlrev_b64 v[58:59], 11, v[6:7]
	v_or_b32_e32 v6, 11, v44
	v_ashrrev_i32_e32 v7, 31, v6
	v_lshlrev_b64 v[60:61], 11, v[6:7]
	v_or_b32_e32 v6, 16, v44
	v_ashrrev_i32_e32 v7, 31, v6
	v_lshlrev_b64 v[62:63], 11, v[6:7]
	v_or_b32_e32 v6, 17, v44
	v_ashrrev_i32_e32 v7, 31, v6
	v_lshlrev_b64 v[64:65], 11, v[6:7]
	v_or_b32_e32 v6, 18, v44
	v_ashrrev_i32_e32 v7, 31, v6
	v_lshlrev_b64 v[66:67], 11, v[6:7]
	v_or_b32_e32 v6, 19, v44
	v_ashrrev_i32_e32 v7, 31, v6
	v_lshlrev_b64 v[68:69], 11, v[6:7]
	v_or_b32_e32 v6, 24, v44
	v_ashrrev_i32_e32 v7, 31, v6
	v_lshlrev_b64 v[70:71], 11, v[6:7]
	v_or_b32_e32 v6, 25, v44
	v_ashrrev_i32_e32 v7, 31, v6
	s_load_dwordx2 s[6:7], s[2:3], 0x50
	v_lshlrev_b64 v[72:73], 11, v[6:7]
	v_or_b32_e32 v6, 26, v44
	v_ashrrev_i32_e32 v7, 31, v6
	v_lshlrev_b64 v[74:75], 11, v[6:7]
	v_or_b32_e32 v6, 27, v44
	v_mov_b32_e32 v35, 0
	v_lshl_add_u32 v3, v4, 1, 0
	v_ashrrev_i32_e32 v45, 31, v44
	v_ashrrev_i32_e32 v7, 31, v6
	s_add_u32 s8, s8, 0x30778000
	v_lshlrev_b32_e32 v34, 5, v1
	v_ashrrev_i32_e32 v33, 31, v5
	v_or_b32_e32 v32, v5, v0
	s_mov_b32 s5, 0
	v_lshlrev_b64 v[46:47], 11, v[44:45]
	v_lshlrev_b64 v[76:77], 11, v[6:7]
	s_addc_u32 s9, s9, 0
	s_waitcnt lgkmcnt(0)
	v_lshl_add_u64 v[78:79], s[6:7], 0, v[34:35]
	s_lshl_b32 s10, s35, 7
	s_lshl_b32 s11, s38, 7
	v_lshlrev_b32_e32 v34, 1, v4
	v_add_u32_e32 v45, v3, v8
	s_mov_b32 s14, 0x5040100
	v_lshlrev_b32_e32 v80, 1, v2
	v_lshlrev_b32_e32 v82, 1, v0
